# attention kt-loop: V fragments prefetched from LDS ahead of exp block; PV MFMAs back-to-back with row-sum fillers
# baseline (speedup 1.0000x reference)
; #define LAS __attribute__((address_space(3)))
; __device__ __forceinline__ unsigned pk2(float lo, float hi) { f32x2 v = {lo, hi}; bf16x2_t b = __builtin_convertvector(v, bf16x2_t); return __builtin_bit_cast(unsigned, b); }
; __device__ __forceinline__ float fexp2(float x) { return __builtin_amdgcn_exp2f(x); }
; #define MFMA16(a, b, c) __builtin_amdgcn_mfma_f32_16x16x32_bf16((a), (b), (c), 0, 0, 0)
; template <class LK> __device__ __forceinline__ void att_qk(AttAcc& A, const LK& lk, const bf16x8 (&bq)[2][2], int nvalid, int g, bf16x8 (&bP)[2][2]) {
;     ...
;         float ls = 0.f;
; #pragma unroll
;         for (int t = 0; t < 4; ++t)
; #pragma unroll
;             for (int r = 0; r < 4; ++r) { s[t][r] = fexp2(s[t][r] - mnew); ls += s[t][r]; }
;         A.l[mm] = A.l[mm] * alpha + ls;
;         if (grew) {
; #pragma unroll
;             for (int d = 0; d < 8; ++d) A.O[mm][d] = A.O[mm][d] * alpha;
;         }
; #pragma unroll
;         for (int k2 = 0; k2 < 2; ++k2) {
;             u32x4 w; w.x = pk2(s[2 * k2][0], s[2 * k2][1]); w.y = pk2(s[2 * k2][2], s[2 * k2][3]); w.z = pk2(s[2 * k2 + 1][0], s[2 * k2 + 1][1]); w.w = pk2(s[2 * k2 + 1][2], s[2 * k2 + 1][3]);
;             bP[mm][k2] = __builtin_bit_cast(bf16x8, w);
;         }
; __device__ __forceinline__ void att_prompt_unit(const Ctx& p, int bh, int qb, LAS unsigned char* lds) {
;     ...
;             const LAS bf16_t* vl = Lc + 64 * KS_STRIDE + q * VS_STRIDE + 8 * g;
; #pragma unroll
;             for (int d = 0; d < 8; ++d)
; #pragma unroll
;                 for (int k2 = 0; k2 < 2; ++k2) {
;                     const bf16x8 vf = *(const LAS bf16x8*)(vl + d * 16 * VS_STRIDE + 32 * k2);
;                     A.O[0][d] = MFMA16(vf, bP[0][k2], A.O[0][d]); A.O[1][d] = MFMA16(vf, bP[1][k2], A.O[1][d]);
;                 }
.LBB0_1795:
	v_add3_u32 v189, s16, v163, v136
	ds_read_b128 v[194:197], v189 offset:17408
	ds_read_b128 v[198:201], v189 offset:17472
	ds_read_b128 v[202:205], v189 offset:19712
	ds_read_b128 v[206:209], v189 offset:19776
	ds_read_b128 v[210:213], v189 offset:22016
	ds_read_b128 v[214:217], v189 offset:22080
	ds_read_b128 v[218:221], v189 offset:24320
	ds_read_b128 v[222:225], v189 offset:24384
	ds_read_b128 v[226:229], v189 offset:26624
	ds_read_b128 v[230:233], v189 offset:26688
	ds_read_b128 v[234:237], v189 offset:28928
	v_sub_f32_e32 v112, v112, v3
	v_sub_f32_e32 v113, v113, v3
	v_sub_f32_e32 v114, v114, v3
	v_sub_f32_e32 v115, v115, v3
	v_sub_f32_e32 v108, v108, v3
	v_sub_f32_e32 v109, v109, v3
	v_sub_f32_e32 v110, v110, v3
	v_sub_f32_e32 v111, v111, v3
	v_sub_f32_e32 v100, v100, v3
	v_sub_f32_e32 v101, v101, v3
	v_sub_f32_e32 v102, v102, v3
	v_sub_f32_e32 v103, v103, v3
	v_sub_f32_e32 v104, v104, v3
	v_sub_f32_e32 v105, v105, v3
	v_sub_f32_e32 v106, v106, v3
	v_sub_f32_e32 v107, v107, v3
	v_sub_f32_e32 v128, v128, v147
	v_sub_f32_e32 v129, v129, v147
	v_sub_f32_e32 v130, v130, v147
	v_sub_f32_e32 v131, v131, v147
	v_sub_f32_e32 v124, v124, v147
	v_sub_f32_e32 v125, v125, v147
	v_sub_f32_e32 v126, v126, v147
	v_sub_f32_e32 v127, v127, v147
	v_sub_f32_e32 v120, v120, v147
	v_sub_f32_e32 v121, v121, v147
	v_sub_f32_e32 v122, v122, v147
	v_sub_f32_e32 v123, v123, v147
	v_sub_f32_e32 v116, v116, v147
	v_sub_f32_e32 v117, v117, v147
	v_sub_f32_e32 v118, v118, v147
	v_sub_f32_e32 v119, v119, v147
	v_exp_f32_e32 v149, v112
	v_exp_f32_e32 v169, v113
	v_exp_f32_e32 v170, v114
	v_exp_f32_e32 v171, v115
	v_exp_f32_e32 v172, v108
	v_exp_f32_e32 v173, v109
	v_exp_f32_e32 v174, v110
	v_exp_f32_e32 v175, v111
	v_exp_f32_e32 v176, v100
	v_exp_f32_e32 v177, v101
	v_exp_f32_e32 v178, v102
	v_exp_f32_e32 v179, v103
	v_exp_f32_e32 v181, v104
	v_exp_f32_e32 v182, v105
	v_exp_f32_e32 v183, v106
	v_exp_f32_e32 v184, v107
	v_exp_f32_e32 v128, v128
	v_exp_f32_e32 v129, v129
	v_exp_f32_e32 v130, v130
	v_exp_f32_e32 v131, v131
	v_exp_f32_e32 v124, v124
	v_exp_f32_e32 v125, v125
	v_exp_f32_e32 v126, v126
	v_exp_f32_e32 v127, v127
	v_exp_f32_e32 v185, v120
	v_exp_f32_e32 v186, v121
	v_exp_f32_e32 v187, v122
	v_exp_f32_e32 v188, v123
	v_exp_f32_e32 v190, v116
	v_exp_f32_e32 v191, v117
	v_exp_f32_e32 v192, v118
	v_exp_f32_e32 v193, v119
	v_cvt_pk_bf16_f32 v100, v149, v169
	v_cvt_pk_bf16_f32 v101, v170, v171
	v_cvt_pk_bf16_f32 v102, v172, v173
	v_cvt_pk_bf16_f32 v103, v174, v175
	v_cvt_pk_bf16_f32 v104, v176, v177
	v_cvt_pk_bf16_f32 v105, v178, v179
	v_cvt_pk_bf16_f32 v106, v181, v182
	v_cvt_pk_bf16_f32 v107, v183, v184
	v_cvt_pk_bf16_f32 v112, v128, v129
	v_cvt_pk_bf16_f32 v113, v130, v131
	v_cvt_pk_bf16_f32 v114, v124, v125
	v_cvt_pk_bf16_f32 v115, v126, v127
	v_cvt_pk_bf16_f32 v108, v185, v186
	v_cvt_pk_bf16_f32 v109, v187, v188
	v_cvt_pk_bf16_f32 v110, v190, v191
	v_cvt_pk_bf16_f32 v111, v192, v193
	s_waitcnt lgkmcnt(0)
	v_mfma_f32_16x16x32_bf16 v[64:67], v[194:197], v[100:103], v[64:67]
	v_add_f32_e32 v117, v149, v169
	v_mfma_f32_16x16x32_bf16 v[60:63], v[194:197], v[112:115], v[60:63]
	v_add_f32_e32 v116, v128, v129
	v_mfma_f32_16x16x32_bf16 v[64:67], v[198:201], v[104:107], v[64:67]
	v_add_f32_e32 v117, v170, v117
	v_mfma_f32_16x16x32_bf16 v[60:63], v[198:201], v[108:111], v[60:63]
	v_add_f32_e32 v116, v130, v116
	ds_read_b128 v[194:197], v189 offset:28992
	ds_read_b128 v[198:201], v189 offset:31232
	v_mfma_f32_16x16x32_bf16 v[56:59], v[202:205], v[100:103], v[56:59]
	v_add_f32_e32 v117, v171, v117
	v_mfma_f32_16x16x32_bf16 v[52:55], v[202:205], v[112:115], v[52:55]
	v_add_f32_e32 v116, v131, v116
	v_mfma_f32_16x16x32_bf16 v[56:59], v[206:209], v[104:107], v[56:59]
	v_add_f32_e32 v117, v172, v117
	v_mfma_f32_16x16x32_bf16 v[52:55], v[206:209], v[108:111], v[52:55]
	v_add_f32_e32 v116, v124, v116
	ds_read_b128 v[202:205], v189 offset:31296
	ds_read_b128 v[206:209], v189 offset:33536
	v_mfma_f32_16x16x32_bf16 v[48:51], v[210:213], v[100:103], v[48:51]
	v_add_f32_e32 v117, v173, v117
	v_mfma_f32_16x16x32_bf16 v[44:47], v[210:213], v[112:115], v[44:47]
	v_add_f32_e32 v116, v125, v116
	v_mfma_f32_16x16x32_bf16 v[48:51], v[214:217], v[104:107], v[48:51]
	v_add_f32_e32 v117, v174, v117
	v_mfma_f32_16x16x32_bf16 v[44:47], v[214:217], v[108:111], v[44:47]
	v_add_f32_e32 v116, v126, v116
	ds_read_b128 v[210:213], v189 offset:33600
	v_mfma_f32_16x16x32_bf16 v[40:43], v[218:221], v[100:103], v[40:43]
	v_add_f32_e32 v117, v175, v117
	v_mfma_f32_16x16x32_bf16 v[36:39], v[218:221], v[112:115], v[36:39]
	v_add_f32_e32 v116, v127, v116
	v_mfma_f32_16x16x32_bf16 v[40:43], v[222:225], v[104:107], v[40:43]
	v_add_f32_e32 v117, v176, v117
	v_mfma_f32_16x16x32_bf16 v[36:39], v[222:225], v[108:111], v[36:39]
	v_add_f32_e32 v116, v185, v116
	v_mfma_f32_16x16x32_bf16 v[28:31], v[226:229], v[100:103], v[28:31]
	v_add_f32_e32 v117, v177, v117
	v_mfma_f32_16x16x32_bf16 v[32:35], v[226:229], v[112:115], v[32:35]
	v_add_f32_e32 v116, v186, v116
	v_mfma_f32_16x16x32_bf16 v[28:31], v[230:233], v[104:107], v[28:31]
	v_add_f32_e32 v117, v178, v117
	v_mfma_f32_16x16x32_bf16 v[32:35], v[230:233], v[108:111], v[32:35]
	v_add_f32_e32 v116, v187, v116
	v_mfma_f32_16x16x32_bf16 v[20:23], v[234:237], v[100:103], v[20:23]
	v_add_f32_e32 v117, v179, v117
	v_mfma_f32_16x16x32_bf16 v[24:27], v[234:237], v[112:115], v[24:27]
	v_add_f32_e32 v116, v188, v116
	s_waitcnt lgkmcnt(4)
	v_mfma_f32_16x16x32_bf16 v[20:23], v[194:197], v[104:107], v[20:23]
	v_add_f32_e32 v117, v181, v117
	v_mfma_f32_16x16x32_bf16 v[24:27], v[194:197], v[108:111], v[24:27]
	v_add_f32_e32 v116, v190, v116
	s_waitcnt lgkmcnt(3)
	v_mfma_f32_16x16x32_bf16 v[16:19], v[198:201], v[100:103], v[16:19]
	v_add_f32_e32 v117, v182, v117
	v_mfma_f32_16x16x32_bf16 v[8:11], v[198:201], v[112:115], v[8:11]
	v_add_f32_e32 v116, v191, v116
	s_waitcnt lgkmcnt(2)
	v_mfma_f32_16x16x32_bf16 v[16:19], v[202:205], v[104:107], v[16:19]
	v_add_f32_e32 v117, v183, v117
	v_mfma_f32_16x16x32_bf16 v[8:11], v[202:205], v[108:111], v[8:11]
	v_add_f32_e32 v116, v192, v116
	s_waitcnt lgkmcnt(1)
	v_mfma_f32_16x16x32_bf16 v[12:15], v[206:209], v[100:103], v[12:15]
	v_add_f32_e32 v117, v184, v117
	v_mfma_f32_16x16x32_bf16 v[4:7], v[206:209], v[112:115], v[4:7]
	v_add_f32_e32 v116, v193, v116
	s_waitcnt lgkmcnt(0)
	v_mfma_f32_16x16x32_bf16 v[12:15], v[210:213], v[104:107], v[12:15]
	v_fmac_f32_e32 v117, v137, v0
	v_mfma_f32_16x16x32_bf16 v[4:7], v[210:213], v[108:111], v[4:7]
	v_fmac_f32_e32 v116, v139, v2
	v_mov_b32_e32 v137, v117
	v_mov_b32_e32 v139, v116
	s_branch .LBB0_1797
